# deferred weight conversion spread over the idle tails of four GEMM phases; prologue keeps only ret_w_in[0]
# speedup vs baseline: 1.0013x; 1.0013x over previous
; #define LAS __attribute__((address_space(3)))
; __device__ __forceinline__ void tr_item(const float* __restrict__ W, int ldw, int k0, int n0, bf16* __restrict__ WT, int ldt, int drow, const float* __restrict__ mu, LAS float* scr, int lane, const float* __restrict__ gs = nullptr) {
; #pragma unroll 8
;     for (int i = 0; i < 32; ++i) { const int kk = 2 * i + (lane >> 5); scr[kk * 33 + (lane & 31)] = W[(size_t)(k0 + kk) * ldw + n0 + (lane & 31)]; }
;     asm volatile("s_waitcnt lgkmcnt(0)" ::: "memory");
;     const int c = lane & 7;
;     float mv[8];
;     if (mu) {
; #pragma unroll
;         for (int e = 0; e < 8; ++e) mv[e] = mu[k0 + 8 * c + e];
;     } else if (gs) {
; #pragma unroll
;         for (int e = 0; e < 8; ++e) mv[e] = gs[k0 + 8 * c + e];
;     }
; #pragma unroll
;     for (int j = 0; j < 4; ++j) {
;         const int n = (lane >> 3) + 8 * j; const LAS float* s = scr + (8 * c) * 33 + n;
;         float f[8];
; #pragma unroll
;         for (int e = 0; e < 8; ++e) f[e] = s[e * 33];
;         bf16* dp = WT + (size_t)(drow + n) * ldt + k0 + 8 * c;
; __device__ __forceinline__ void ph_p0(const Params& p, LAS unsigned char* lds, int tid, int lane, int wave) {
;     ...
;     const int gw = blockIdx.x * NWAVES + wave, NGW = gridDim.x * NWAVES;
;     constexpr int C_WIN = 2 * 16 * 192, C_WOUT = 2 * 32 * 32, C_RKV = 2 * 3 * 512, C_W1 = 2 * 32, C_A1 = 2 * 32, C_G1 = 2 * 80, C_V1 = 16, C_WO = 2 * 512, C_WUG = 4 * 16 * 176, C_WD = 4 * 44 * 32;
;     constexpr int NITEMS = C_WIN + C_WOUT + C_RKV + C_W1 + C_A1 + C_G1 + C_V1 + C_WO + C_WUG + C_WD;
;     for (int it = gw; it < NITEMS; it += NGW) {
;         int r = it;
;         if (r < C_WIN) { const int j = r / 3072, q = r % 3072, kb = q / 192, nb = q % 192;
.LBB0_1410:
	s_and_b64 vcc, exec, s[40:41]
	v_readlane_b32 s40, v254, 60
	v_readlane_b32 s30, v254, 56
	v_readlane_b32 s34, v254, 58
	v_readlane_b32 s41, v254, 61
	v_readlane_b32 s44, v255, 0
	v_readlane_b32 s45, v255, 1
	v_readlane_b32 s48, v255, 4
	v_readlane_b32 s49, v255, 5
	v_readlane_b32 s50, v255, 6
	v_readlane_b32 s51, v255, 7
	v_readlane_b32 s52, v255, 8
	v_readlane_b32 s53, v255, 9
	v_readlane_b32 s31, v254, 57
	v_readlane_b32 s35, v254, 59
	v_readlane_b32 s42, v254, 62
	v_readlane_b32 s43, v254, 63
	v_readlane_b32 s46, v255, 2
	v_readlane_b32 s47, v255, 3
	v_readlane_b32 s54, v255, 10
	v_readlane_b32 s55, v255, 11
	s_cbranch_vccz .LBB0_1548
	v_readlane_b32 s0, v255, 14
	s_and_b32 s0, 0xffff, s0
	s_cmp_lg_u32 s0, 0
	s_cbranch_scc1 .LBB0_1547
	s_load_dword s6, s[88:89], 0x0
	v_readlane_b32 s0, v253, 1
	v_readlane_b32 s1, v255, 15
	s_add_i32 s2, s1, s0
	s_waitcnt lgkmcnt(0)
	s_lshl_b32 s24, s6, 3
	s_cmp_ge_u32 s100, 4
	s_cselect_b32 s24, 0x740, s24
	s_cselect_b32 s101, 0xc0, 0
	s_cmp_eq_u32 s100, 6
	s_cselect_b32 s24, 0x2a0, s24
	s_cselect_b32 s101, 0x560, s101
	s_cmp_eq_u32 s100, 7
	s_cselect_b32 s24, 0x320, s24
	s_cselect_b32 s101, 0x4e0, s101
	s_sub_i32 s2, s2, s101
	s_cmpk_gt_i32 s2, 0x732f
	s_cbranch_scc1 .LBB0_1498
	s_lshl_b32 s0, s1, 14
	v_and_b32_e32 v16, 31, v194
	v_and_b32_e32 v0, 7, v194
	v_lshrrev_b32_e32 v17, 3, v238
	s_add_i32 s0, s0, 0
	v_lshlrev_b32_e32 v2, 2, v16
	v_mul_u32_u24_e32 v3, 0x420, v0
	v_lshlrev_b32_e32 v4, 2, v17
	s_waitcnt vmcnt(0)
	v_add_u32_e32 v18, s0, v2
	v_add3_u32 v19, s0, v3, v4
	v_readlane_b32 s0, v253, 8
	v_lshlrev_b32_e32 v20, 3, v0
	v_lshlrev_b32_e32 v0, 4, v0
	v_readlane_b32 s1, v253, 9
	v_readlane_b32 s8, v254, 5
	v_lshrrev_b32_e32 v14, 5, v238
	v_lshl_add_u64 v[4:5], s[0:1], 0, v[0:1]
	v_lshlrev_b32_e32 v0, 12, v17
	v_mov_b32_e32 v3, v1
	v_readlane_b32 s20, v254, 17
	v_readlane_b32 s21, v254, 18
	v_or_b32_e32 v21, 8, v17
	v_or_b32_e32 v38, 16, v17
	v_or_b32_e32 v39, 24, v17
	v_lshl_add_u64 v[22:23], v[4:5], 0, v[0:1]
	v_lshl_add_u64 v[24:25], s[20:21], 0, v[2:3]
	v_mov_b32_e32 v15, v14
	s_mov_b32 s3, s2
	v_readlane_b32 s9, v254, 6
	v_readlane_b32 s10, v254, 7
	v_readlane_b32 s11, v254, 8
	v_readlane_b32 s12, v254, 9
	v_readlane_b32 s13, v254, 10
	v_readlane_b32 s14, v254, 11
	v_readlane_b32 s15, v254, 12
	v_readlane_b32 s16, v254, 13
	v_readlane_b32 s17, v254, 14
	v_readlane_b32 s18, v254, 15
	v_readlane_b32 s19, v254, 16
	v_readlane_b32 s22, v254, 19
	v_readlane_b32 s23, v254, 20
	s_branch .LBB0_1416

; __device__ __forceinline__ void ph_p0(const Params& p, LAS unsigned char* lds, int tid, int lane, int wave) {
;     ...
;     for (int it = gw; it < NITEMS; it += NGW) {
;         int r = it;
;         if (r < C_WIN) { const int j = r / 3072, q = r % 3072, kb = q / 192, nb = q % 192;
;             tr_item(p.in[I_RWIN] + (size_t)j * D * RWIN, RWIN, 64 * kb, 32 * nb, (bf16*)(ws + WS_WIN + j * SZ_WIN), D, 32 * nb, nullptr, scr, lane, p.in[I_NMIX] + (size_t)(2 * j) * D); continue; }
;         r -= C_WIN;
;         if (r < C_WOUT) { const int j = r / 1024, q = r % 1024, kb = q / 32, nb = q % 32;
;             tr_item(p.in[I_RWOUT] + (size_t)j * RV * D, D, 64 * kb, 32 * nb, (bf16*)(ws + WS_WOUT + j * SZ_WOUT), RV, 32 * nb, nullptr, scr, lane); continue; }
;         r -= C_WOUT;
;         if (r < C_RKV) { const int j = r / 1536, q = r % 1536, s = q / 512, q2 = q % 512, kb = q2 / 32, nb = q2 % 32, c = (s == 0 ? 0 : (s == 1 ? 2 : 3));
;             tr_item(p.in[I_WRKV] + (size_t)(j * 3 + s) * D * D, D, 64 * kb, 32 * nb, (bf16*)(ws + WS_WRW + j * SZ_WRW), KRW, s * 1024 + 32 * nb, p.in[I_MU] + (size_t)(j * 6 + c) * D, scr, lane); continue; }
;         r -= C_RKV;
;         if (r < C_W1) { const int j = r / 32, q = r % 32, kb = q / 2, nb = q % 2;
;             tr_item(p.in[I_W1] + (size_t)j * D * LW, LW, 64 * kb, 32 * nb, (bf16*)(ws + WS_WRW + j * SZ_WRW), KRW, 3072 + 32 * nb, p.in[I_MU] + (size_t)(j * 6 + 1) * D, scr, lane); continue; }
;         r -= C_W1;
;         if (r < C_A1) { const int j = r / 32, q = r % 32, kb = q / 2, nb = q % 2;
;             tr_item(p.in[I_A1] + (size_t)j * D * LA, LA, 64 * kb, 32 * nb, (bf16*)(ws + WS_WRW + j * SZ_WRW), KRW, 3136 + 32 * nb, p.in[I_MU] + (size_t)(j * 6 + 4) * D, scr, lane); continue; }
;         r -= C_A1;
;         if (r < C_G1) { const int j = r / 80, q = r % 80, kb = q / 5, nb = q % 5;
;             tr_item(p.in[I_G1] + (size_t)j * D * LG, LG, 64 * kb, 32 * nb, (bf16*)(ws + WS_WRW + j * SZ_WRW), KRW, 3200 + 32 * nb, p.in[I_MU] + (size_t)(j * 6 + 5) * D, scr, lane); continue; }
;         r -= C_G1;
;         if (r < C_V1) { const int kb = r;
;             tr_item(p.in[I_V1], LV, 64 * kb, 0, (bf16*)(ws + WS_WRW + 1 * SZ_WRW), KRW, 3360, p.in[I_MU] + (size_t)(1 * 6 + 3) * D, scr, lane); continue; }
;         r -= C_V1;
;         if (r < C_WO) { const int j = r / 512, q = r % 512, kb = q / 32, nb = q % 32;
.LBB0_1416:
	s_mov_b32 s101, 5
	s_cmp_lt_u32 s3, 0x6830
	s_cselect_b32 s101, 7, s101
	s_cmp_lt_u32 s3, 0x62b0
	s_cselect_b32 s101, 4, s101
	s_cmp_lt_u32 s3, 0x5d30
	s_cselect_b32 s101, 5, s101
	s_cmp_lt_u32 s3, 0x4730
	s_cselect_b32 s101, 7, s101
	s_cmp_lt_u32 s3, 0x3c30
	s_cselect_b32 s101, 4, s101
	s_cmp_lt_u32 s3, 0x3130
	s_cselect_b32 s101, 5, s101
	s_cmp_lt_u32 s3, 0x2f30
	s_cselect_b32 s101, 6, s101
	s_cmp_lt_u32 s3, 0x2d30
	s_cselect_b32 s101, 5, s101
	s_cmp_lt_u32 s3, 0x2cd0
	s_cselect_b32 s101, 6, s101
	s_cmp_lt_u32 s3, 0x2c80
	s_cselect_b32 s101, 5, s101
	s_cmp_lt_u32 s3, 0x2c60
	s_cselect_b32 s101, 6, s101
	s_cmp_lt_u32 s3, 0x2c40
	s_cselect_b32 s101, 5, s101
	s_cmp_lt_u32 s3, 0x2c20
	s_cselect_b32 s101, 6, s101
	s_cmp_lt_u32 s3, 0x2c00
	s_cselect_b32 s101, 5, s101
	s_cmp_lt_u32 s3, 0x2600
	s_cselect_b32 s101, 6, s101
	s_cmp_lt_u32 s3, 0x2000
	s_cselect_b32 s101, 4, s101
	s_cmp_lt_u32 s3, 0xc00
	s_cselect_b32 s101, 0, s101
	s_cmp_lg_u32 s101, s100
	s_cbranch_scc1 .LBB0_1415
	s_cmpk_gt_i32 s3, 0x17ff
	s_mov_b64 s[0:1], -1
	s_cbranch_scc0 .LBB0_1468
	s_cmpk_gt_u32 s3, 0x1fff
	s_cbranch_scc0 .LBB0_1484
	s_cmpk_gt_u32 s3, 0x2bff
	s_cbranch_scc0 .LBB0_1463
	s_cmpk_gt_u32 s3, 0x2c3f
	s_cbranch_scc0 .LBB0_1458
	s_cmpk_gt_u32 s3, 0x2c7f
	s_cbranch_scc0 .LBB0_1453
	s_cmpk_gt_u32 s3, 0x2d1f
	s_cbranch_scc0 .LBB0_1448
	s_cmpk_gt_u32 s3, 0x2d2f
	s_cbranch_scc0 .LBB0_1443
	s_cmpk_gt_u32 s3, 0x312f
	s_cbranch_scc0 .LBB0_1438
	s_cmpk_gt_u32 s3, 0x5d2f
	s_cbranch_scc0 .LBB0_1428
	s_add_i32 s0, s3, 0xa2d0
	s_and_b32 s1, s0, 0xffff
	s_mul_i32 s1, s1, 0xba2f
	s_lshr_b32 s1, s1, 26
	s_mul_i32 s4, s1, 0x580
	s_sub_i32 s0, s0, s4
	v_readlane_b32 s8, v252, 0
	s_and_b32 s0, s0, 0xffff
	s_mul_i32 s4, s1, 0xb00000
	v_readlane_b32 s14, v252, 6
	v_readlane_b32 s9, v252, 1
	v_readlane_b32 s15, v252, 7
	s_add_u32 s7, s14, s4
	s_addc_u32 s9, s15, 0
	s_lshl_b32 s4, s0, 1
	s_lshl_b32 s0, s0, 5
	s_and_b32 s0, s0, 0x3e0
	s_and_b32 s4, s4, 0xfc0
	s_lshl_b32 s8, s0, 2
	s_add_u32 s8, s7, s8
	s_addc_u32 s9, s9, 0
	v_lshlrev_b32_e32 v0, 2, v16
	s_mov_b32 s5, 1
	v_lshl_add_u64 v[2:3], s[8:9], 0, v[0:1]
	s_mov_b32 s7, s4
	s_mov_b32 s8, 0
	s_mov_b32 s9, 32
	v_readlane_b32 s10, v252, 2
	v_readlane_b32 s11, v252, 3
	v_readlane_b32 s12, v252, 4
	v_readlane_b32 s13, v252, 5

; __global__ void __launch_bounds__(NTHR, 2) mega(Params p, int lo, int hi) {
;     ...
;     for (int ph = lo; ph < hi; ++ph) {
;         int lid_; asm volatile("v_mbcnt_lo_u32_b32 %0, -1, 0\n\tv_mbcnt_hi_u32_b32 %0, -1, %0" : "=v"(lid_));
;         int tid = wave0 * 64 + lid_; asm volatile("" : "+v"(tid));
;         const int lane = tid & 63, wave = __builtin_amdgcn_readfirstlane(tid >> 6);
;         unsigned char* ws = p.ws;
;         const Ph P = phase_at(ph);
;         const int li = P.layer, jl = li >> 1;
;         const bf16* gA = nullptr; const bf16* gB = nullptr; int gN = 0, gK = 0; EpiAnyT<0> E{}; E.jl = jl; E.ws = ws; E.slot = -1; E.amul = 1.f; E.li = li; E.ldsb = lds; bool is_gemm = false;
;         switch (P.op) {
;         case OP_P0: ph_p0(p, lds, tid, lane, wave); break;
.Lsub_not1:
	s_cmp_ge_u32 s100, 4
	s_cbranch_scc1 .Lp0b_ret
	s_cmp_eq_u32 s100, 0
	s_cbranch_scc0 .Lsub_fin
	s_mov_b32 s0, 24
	s_cmp_eq_u32 s56, 1
	s_cselect_b32 s101, 4, 0
	s_cmp_eq_u32 s56, 16
	s_cselect_b32 s101, 5, s101
	s_cmp_eq_u32 s56, 5
	s_cselect_b32 s101, 6, s101
	s_cselect_b32 s0, 0xac, s0
	s_cmp_eq_u32 s56, 8
	s_cselect_b32 s101, 7, s101
	s_cselect_b32 s0, 0x9c, s0
	s_cmp_eq_u32 s101, 0
	s_cbranch_scc1 .Lsub_fin
	v_readlane_b32 s1, v254, 37
	s_cmp_lt_u32 s1, s0
	s_cbranch_scc1 .Lsub_fin
	v_writelane_b32 v255, s56, 62
	s_mov_b32 s100, s101
	s_mov_b32 s56, 0
	s_branch .Lsub_tramp1
